# additionally: norm phases issue the next chunk's parameter loads ahead of the output store (loads renamed into scratch registers)
# baseline (speedup 1.0000x reference)
; #define IN(k) ((const float*)kload(8 * (k)))
; #define OUTP() ((float*)kload(272))
; #define WSP() ((unsigned char*)kload(280))
; DI unsigned pk2(float lo, float hi) { return f2bf(lo) | (f2bf(hi) << 16); }
; #define BIDX() sgpr_opaque((int)__builtin_amdgcn_workgroup_id_x())
; #define GDIM() sgpr_opaque((int)__ockl_get_num_groups(0))
; DI void phase_norm(int layer, const float* g, int sidx, bf16_t* dst, bool first) {
;     const int tid0 = tid_opaque(); const int lane = tid0 & 63, wave = tid0 >> 6; unsigned char* ws = WSP();
;     const float* zcs = first ? IN(2) : (const float*)(ws + WS_ZC); const float* zls = first ? IN(0) : (const float*)OUTP();
;     const int nw = GDIM() * 8;
;     for (int m0 = BIDX() * 8 + wave; m0 < M; m0 += 2 * nw) {
;         const int m1 = m0 + nw; const bool has1 = m1 < M; const int m1c = has1 ? m1 : m0;
;         const float* z0 = zrow_src(zcs, zls, m0); const float* z1 = zrow_src(zcs, zls, m1c);
;         f32x4 v0[4], v1[4]; float ss0 = 0.f, ss1 = 0.f;
; #pragma unroll
;         for (int j = 0; j < 4; ++j) { v0[j] = *(const f32x4*)(z0 + 4 * lane + 256 * j); v1[j] = *(const f32x4*)(z1 + 4 * lane + 256 * j); }
; #pragma unroll
;         for (int j = 0; j < 4; ++j) { ss0 += v0[j][0] * v0[j][0] + v0[j][1] * v0[j][1] + v0[j][2] * v0[j][2] + v0[j][3] * v0[j][3]; ss1 += v1[j][0] * v1[j][0] + v1[j][1] * v1[j][1] + v1[j][2] * v1[j][2] + v1[j][3] * v1[j][3]; }
; #pragma unroll
;         for (int o = 1; o < 64; o <<= 1) { ss0 += __shfl_xor(ss0, o); ss1 += __shfl_xor(ss1, o); }
; #pragma unroll
;         for (int r = 0; r < 2; ++r) {
;             if (r == 1 && !has1) break;
;             const int m = r ? m1 : m0; const int b = m / T, t = m - b * T; const int who = t < LC ? 8 : b;
;             const float* sh = modp(ws, layer, who, sidx); const float* sc = modp(ws, layer, who, sidx + 1);
;             const float rstd = rsqrtf((r ? ss1 : ss0) * (1.f / D) + 1e-6f);
; #pragma unroll
;             for (int j = 0; j < 4; ++j) { const int c = 4 * lane + 256 * j;
;                 const f32x4 gg = *(const f32x4*)(g + c), s1 = *(const f32x4*)(sc + c), s0 = *(const f32x4*)(sh + c);
;                 f32x4 y = (r ? v1[j] : v0[j]) * rstd * gg; y = y * (s1 + 1.f) + s0;
;                 u32x2 w; w.x = pk2(y[0], y[1]); w.y = pk2(y[2], y[3]);
;                 *(u32x2*)(dst + (size_t)m * D + c) = w; }
.LBB0_51:
	s_mov_b32 s2, 0x78787879
	v_mul_hi_i32 v0, v30, s2
	v_lshrrev_b32_e32 v2, 31, v0
	v_ashrrev_i32_e32 v0, 11, v0
	v_add_u32_e32 v5, v0, v2
	s_movk_i32 s2, 0xef00
	v_mad_i32_i24 v0, v5, s2, v30
	s_movk_i32 s2, 0x100
	v_cmp_gt_i32_e64 s[4:5], s2, v0
	s_movk_i32 s2, 0xff
	v_cmp_lt_i32_e32 vcc, s2, v0
	v_mov_b64_e32 v[6:7], s[12:13]
	s_and_saveexec_b64 s[2:3], vcc
	s_xor_b64 s[2:3], exec, s[2:3]
	v_mul_i32_i24_e32 v0, 0xffffef00, v5
	v_lshl_add_u32 v0, v5, 12, v0
	s_movk_i32 s6, 0xff00
	v_add3_u32 v8, v30, v0, s6
	v_mov_b64_e32 v[6:7], s[14:15]
	s_andn2_saveexec_b64 s[2:3], s[2:3]
	v_lshl_add_u32 v8, v5, 8, v0
	s_or_b64 exec, exec, s[2:3]
	v_add_u32_e32 v46, s24, v30
	s_mov_b32 s2, 0x8800
	v_cmp_gt_i32_e32 vcc, s2, v46
	s_mov_b32 s2, 0x78787879
	s_nop 0
	v_cndmask_b32_e32 v2, v30, v46, vcc
	v_mul_hi_i32 v0, v2, s2
	v_lshrrev_b32_e32 v3, 31, v0
	v_ashrrev_i32_e32 v0, 11, v0
	v_add_u32_e32 v0, v0, v3
	s_movk_i32 s2, 0xef00
	v_mad_i32_i24 v9, v0, s2, v2
	s_movk_i32 s2, 0xff
	v_cmp_lt_i32_e64 s[6:7], s2, v9
	v_mov_b64_e32 v[2:3], s[12:13]
	s_and_saveexec_b64 s[2:3], s[6:7]
	s_xor_b64 s[2:3], exec, s[2:3]
	v_lshlrev_b32_e32 v0, 12, v0
	s_movk_i32 s6, 0xff00
	v_add3_u32 v4, v0, v9, s6
	v_mov_b64_e32 v[2:3], s[14:15]
	s_andn2_saveexec_b64 s[2:3], s[2:3]
	v_lshl_add_u32 v4, v0, 8, v9
	s_or_b64 exec, exec, s[2:3]
	v_ashrrev_i32_e32 v9, 31, v8
	v_lshlrev_b64 v[8:9], 12, v[8:9]
	v_lshl_add_u64 v[6:7], v[6:7], 0, v[8:9]
	v_lshlrev_b32_e32 v0, 2, v32
	v_lshl_add_u64 v[6:7], v[6:7], 0, v[0:1]
	global_load_dwordx4 v[56:59], v[6:7], off
	global_load_dwordx4 v[26:29], v[6:7], off offset:1024
	s_waitcnt lgkmcnt(0)
	global_load_dwordx4 v[14:17], v[6:7], off offset:2048
	s_nop 0
	global_load_dwordx4 v[6:9], v[6:7], off offset:3072
	v_cndmask_b32_e64 v5, v5, 8, s[4:5]
	v_add_u32_e32 v5, s25, v5
	v_mul_i32_i24_e32 v10, 6, v5
	v_ashrrev_i32_e32 v11, 31, v10
	v_lshlrev_b64 v[10:11], 12, v[10:11]
	v_lshl_add_u64 v[10:11], s[16:17], 0, v[10:11]
	s_mov_b64 s[2:3], 0x4000
	v_lshl_add_u64 v[48:49], v[10:11], 0, s[2:3]
	s_mov_b64 s[2:3], 0x3000
	v_lshl_add_u64 v[12:13], v[48:49], 0, v[0:1]
	v_lshl_add_u64 v[72:73], v[10:11], 0, s[2:3]
	global_load_dwordx4 v[60:63], v[12:13], off
	global_load_dwordx4 v[64:67], v[34:35], off
	v_lshl_add_u64 v[10:11], v[72:73], 0, v[0:1]
	global_load_dwordx4 v[68:71], v[10:11], off
	s_mov_b32 s2, 0x800000
	v_mov_b32_e32 v41, v1
	s_waitcnt vmcnt(0)
	v_mov_b32_e32 v12, v57
	v_mov_b32_e32 v13, v27
	v_mov_b32_e32 v10, v56
	v_mov_b32_e32 v11, v26
	v_mov_b32_e32 v24, v15
	v_mov_b32_e32 v25, v7
	v_pk_mul_f32 v[12:13], v[12:13], v[12:13]
	v_mov_b32_e32 v18, v58
	v_mov_b32_e32 v19, v28
	v_mov_b32_e32 v22, v14
	v_mov_b32_e32 v23, v6
	v_pk_mul_f32 v[24:25], v[24:25], v[24:25]
	v_pk_fma_f32 v[10:11], v[10:11], v[10:11], v[12:13]
	v_mov_b32_e32 v20, v59
	v_mov_b32_e32 v21, v29
	v_mov_b32_e32 v74, v16
	v_mov_b32_e32 v75, v8
	v_pk_fma_f32 v[12:13], v[22:23], v[22:23], v[24:25]
	v_pk_fma_f32 v[10:11], v[18:19], v[18:19], v[10:11]
	v_mov_b32_e32 v76, v17
	v_mov_b32_e32 v77, v9
	v_pk_fma_f32 v[12:13], v[74:75], v[74:75], v[12:13]
	v_pk_fma_f32 v[10:11], v[20:21], v[20:21], v[10:11]
	v_pk_fma_f32 v[12:13], v[76:77], v[76:77], v[12:13]
	v_add_f32_e32 v5, v10, v11
	v_add_f32_e32 v5, v5, v12
	v_add_f32_e32 v5, v5, v13
	ds_bpermute_b32 v10, v33, v5
	v_pk_add_f32 v[62:63], v[62:63], 1.0 op_sel_hi:[1,0]
	v_pk_add_f32 v[60:61], v[60:61], 1.0 op_sel_hi:[1,0]
	s_waitcnt lgkmcnt(0)
	v_add_f32_e32 v5, v5, v10
	ds_bpermute_b32 v10, v50, v5
	s_waitcnt lgkmcnt(0)
	v_add_f32_e32 v5, v5, v10
	ds_bpermute_b32 v10, v51, v5
	s_waitcnt lgkmcnt(0)
	v_add_f32_e32 v5, v5, v10
	ds_bpermute_b32 v10, v52, v5
	s_waitcnt lgkmcnt(0)
	v_add_f32_e32 v10, v5, v10
	ds_bpermute_b32 v11, v53, v10
	v_ashrrev_i32_e32 v5, 31, v4
	v_lshlrev_b64 v[4:5], 12, v[4:5]
	v_lshl_add_u64 v[2:3], v[2:3], 0, v[4:5]
	v_lshl_add_u64 v[2:3], v[2:3], 0, v[0:1]
	s_waitcnt lgkmcnt(0)
	v_add_f32_e32 v10, v10, v11
	ds_bpermute_b32 v11, v54, v10
	global_load_dwordx4 v[22:25], v[2:3], off
	global_load_dwordx4 v[18:21], v[2:3], off offset:1024
	s_waitcnt lgkmcnt(0)
	v_add_f32_e32 v4, v10, v11
	v_fmamk_f32 v4, v4, 0x3a800000, v183
	v_mul_f32_e32 v5, 0x4b800000, v4
	v_cmp_gt_f32_e64 s[4:5], s2, v4
	s_nop 1
	v_cndmask_b32_e64 v4, v4, v5, s[4:5]
	v_rsq_f32_e32 v31, v4
	global_load_dwordx4 v[10:13], v[2:3], off offset:2048
	s_nop 0
	global_load_dwordx4 v[2:5], v[2:3], off offset:3072
	v_mul_f32_e32 v43, 0x45800000, v31
	v_cndmask_b32_e64 v74, v31, v43, s[4:5]
	v_pk_mul_f32 v[58:59], v[58:59], v[74:75] op_sel_hi:[1,0]
	v_pk_mul_f32 v[56:57], v[56:57], v[74:75] op_sel_hi:[1,0]
	v_pk_mul_f32 v[58:59], v[66:67], v[58:59]
	v_pk_mul_f32 v[56:57], v[64:65], v[56:57]
	v_pk_fma_f32 v[58:59], v[62:63], v[58:59], v[70:71]
	v_pk_fma_f32 v[56:57], v[60:61], v[56:57], v[68:69]
	v_bfe_u32 v45, v58, 16, 1
	v_bfe_u32 v31, v56, 16, 1
	v_bfe_u32 v43, v57, 16, 1
	v_bfe_u32 v47, v59, 16, 1
	v_add3_u32 v31, v56, v31, s31
	v_add3_u32 v45, v58, v45, s31
	v_add3_u32 v43, v57, v43, s31
	v_add3_u32 v47, v59, v47, s31
	v_lshrrev_b32_e32 v31, 16, v31
	v_lshrrev_b32_e32 v45, 16, v45
	v_and_or_b32 v56, v43, s0, v31
	v_and_or_b32 v57, v47, s0, v45
	v_lshl_add_u64 v[60:61], v[48:49], 0, v[40:41]
	global_load_dwordx4 v[80:83], v[34:35], off offset:1024
	v_lshl_add_u64 v[64:65], v[72:73], 0, v[40:41]
	global_load_dwordx4 v[84:87], v[60:61], off
	v_pk_mul_f32 v[28:29], v[28:29], v[74:75] op_sel_hi:[1,0]
	global_load_dwordx4 v[88:91], v[64:65], off
	v_pk_mul_f32 v[26:27], v[26:27], v[74:75] op_sel_hi:[1,0]
	v_mov_b32_e32 v43, v1
	v_pk_mul_f32 v[16:17], v[16:17], v[74:75] op_sel_hi:[1,0]
	v_pk_mul_f32 v[14:15], v[14:15], v[74:75] op_sel_hi:[1,0]
	v_pk_mul_f32 v[8:9], v[8:9], v[74:75] op_sel_hi:[1,0]
	v_pk_mul_f32 v[6:7], v[6:7], v[74:75] op_sel_hi:[1,0]
	global_store_dwordx2 v[38:39], v[56:57], off
	s_waitcnt vmcnt(3)
; DI unsigned pk2(float lo, float hi) { return f2bf(lo) | (f2bf(hi) << 16); }
; DI const float* modp(const unsigned char* ws, int layer, int who, int idx) { return (const float*)(ws + WS_MOD) + ((size_t)(layer * 9 + who) * 6 + idx) * D; }
; DI void phase_norm(int layer, const float* g, int sidx, bf16_t* dst, bool first) {
;     ...
;         for (int j = 0; j < 4; ++j) { ss0 += v0[j][0] * v0[j][0] + v0[j][1] * v0[j][1] + v0[j][2] * v0[j][2] + v0[j][3] * v0[j][3]; ss1 += v1[j][0] * v1[j][0] + v1[j][1] * v1[j][1] + v1[j][2] * v1[j][2] + v1[j][3] * v1[j][3]; }
; #pragma unroll
;         for (int o = 1; o < 64; o <<= 1) { ss0 += __shfl_xor(ss0, o); ss1 += __shfl_xor(ss1, o); }
;     ...
;             const float* sh = modp(ws, layer, who, sidx); const float* sc = modp(ws, layer, who, sidx + 1);
;             const float rstd = rsqrtf((r ? ss1 : ss0) * (1.f / D) + 1e-6f);
; #pragma unroll
;             for (int j = 0; j < 4; ++j) { const int c = 4 * lane + 256 * j;
;                 const f32x4 gg = *(const f32x4*)(g + c), s1 = *(const f32x4*)(sc + c), s0 = *(const f32x4*)(sh + c);
;                 f32x4 y = (r ? v1[j] : v0[j]) * rstd * gg; y = y * (s1 + 1.f) + s0;
;                 u32x2 w; w.x = pk2(y[0], y[1]); w.y = pk2(y[2], y[3]);
;                 *(u32x2*)(dst + (size_t)m * D + c) = w; }
	v_mov_b64_e32 v[56:57], v[80:81]
	v_mov_b64_e32 v[58:59], v[82:83]
	v_pk_mul_f32 v[26:27], v[56:57], v[26:27]
	v_pk_mul_f32 v[28:29], v[58:59], v[28:29]
	s_waitcnt vmcnt(2)
	v_mov_b64_e32 v[60:61], v[84:85]
	v_mov_b64_e32 v[62:63], v[86:87]
	v_pk_add_f32 v[56:57], v[62:63], 1.0 op_sel_hi:[1,0]
	v_pk_add_f32 v[58:59], v[60:61], 1.0 op_sel_hi:[1,0]
	s_waitcnt vmcnt(1)
	v_mov_b64_e32 v[64:65], v[88:89]
	v_mov_b64_e32 v[66:67], v[90:91]
	v_pk_fma_f32 v[28:29], v[56:57], v[28:29], v[66:67]
	v_pk_fma_f32 v[26:27], v[58:59], v[26:27], v[64:65]
	v_bfe_u32 v47, v28, 16, 1
	v_bfe_u32 v31, v26, 16, 1
	v_bfe_u32 v45, v27, 16, 1
	v_bfe_u32 v55, v29, 16, 1
	v_add3_u32 v26, v26, v31, s31
	v_add3_u32 v28, v28, v47, s31
	v_add3_u32 v27, v27, v45, s31
	v_add3_u32 v29, v29, v55, s31
	v_lshrrev_b32_e32 v26, 16, v26
	v_lshrrev_b32_e32 v28, 16, v28
	v_and_or_b32 v26, v27, s0, v26
	v_and_or_b32 v27, v29, s0, v28
	v_lshl_add_u64 v[56:57], v[48:49], 0, v[42:43]
	global_load_dwordx4 v[80:83], v[34:35], off offset:2048
	v_lshl_add_u64 v[60:61], v[72:73], 0, v[42:43]
	global_load_dwordx4 v[84:87], v[56:57], off
	v_mov_b32_e32 v45, v1
	global_load_dwordx4 v[88:91], v[60:61], off
	global_store_dwordx2 v[38:39], v[26:27], off offset:512
	s_waitcnt vmcnt(3)
	v_mov_b64_e32 v[26:27], v[80:81]
	v_mov_b64_e32 v[28:29], v[82:83]
	v_pk_mul_f32 v[14:15], v[26:27], v[14:15]
	v_pk_mul_f32 v[16:17], v[28:29], v[16:17]
	s_waitcnt vmcnt(2)
	v_mov_b64_e32 v[56:57], v[84:85]
	v_mov_b64_e32 v[58:59], v[86:87]
	v_pk_add_f32 v[26:27], v[58:59], 1.0 op_sel_hi:[1,0]
	v_pk_add_f32 v[28:29], v[56:57], 1.0 op_sel_hi:[1,0]
	s_waitcnt vmcnt(1)
	v_mov_b64_e32 v[60:61], v[88:89]
	v_mov_b64_e32 v[62:63], v[90:91]
	v_pk_fma_f32 v[16:17], v[26:27], v[16:17], v[62:63]
	v_pk_fma_f32 v[14:15], v[28:29], v[14:15], v[60:61]
	v_bfe_u32 v28, v16, 16, 1
	v_bfe_u32 v26, v14, 16, 1
	v_bfe_u32 v27, v15, 16, 1
	v_bfe_u32 v29, v17, 16, 1
	v_add3_u32 v14, v14, v26, s31
	v_add3_u32 v16, v16, v28, s31
	v_add3_u32 v15, v15, v27, s31
	v_add3_u32 v17, v17, v29, s31
	v_lshrrev_b32_e32 v14, 16, v14
	v_lshrrev_b32_e32 v16, 16, v16
	v_and_or_b32 v14, v15, s0, v14
	v_and_or_b32 v15, v17, s0, v16
	global_store_dwordx2 v[38:39], v[14:15], off offset:1024
	v_lshl_add_u64 v[14:15], v[48:49], 0, v[44:45]
	global_load_dwordx4 v[26:29], v[34:35], off offset:3072
	global_load_dwordx4 v[56:59], v[14:15], off
	v_lshl_add_u64 v[14:15], v[72:73], 0, v[44:45]
	global_load_dwordx4 v[60:63], v[14:15], off
	v_mul_f32_e32 v14, v23, v23
	v_mul_f32_e32 v15, v19, v19
	v_mul_f32_e32 v16, v11, v11
	v_fmac_f32_e32 v14, v22, v22
	v_fmac_f32_e32 v15, v18, v18
	v_mul_f32_e32 v17, v3, v3
	v_fmac_f32_e32 v16, v10, v10
	v_fmac_f32_e32 v14, v24, v24
	v_fmac_f32_e32 v15, v20, v20
	v_fmac_f32_e32 v17, v2, v2
	v_fmac_f32_e32 v16, v12, v12
	v_fmac_f32_e32 v14, v25, v25
	v_fmac_f32_e32 v15, v21, v21
	v_fmac_f32_e32 v17, v4, v4
	v_fmac_f32_e32 v16, v13, v13
	v_add_f32_e32 v14, v14, v15
	v_fmac_f32_e32 v17, v5, v5
	v_add_f32_e32 v14, v14, v16
	v_add_f32_e32 v14, v14, v17
	ds_bpermute_b32 v15, v33, v14
	s_waitcnt lgkmcnt(0)
	v_add_f32_e32 v14, v14, v15
	ds_bpermute_b32 v15, v50, v14
	s_waitcnt lgkmcnt(0)
	v_add_f32_e32 v14, v14, v15
	ds_bpermute_b32 v15, v51, v14
	s_waitcnt lgkmcnt(0)
	v_add_f32_e32 v14, v14, v15
	ds_bpermute_b32 v15, v52, v14
	s_waitcnt lgkmcnt(0)
	v_add_f32_e32 v14, v14, v15
	ds_bpermute_b32 v15, v53, v14
	s_waitcnt lgkmcnt(0)
	v_add_f32_e32 v14, v14, v15
	ds_bpermute_b32 v15, v54, v14
	s_waitcnt vmcnt(2)
	v_pk_mul_f32 v[6:7], v[6:7], v[26:27]
	v_pk_mul_f32 v[8:9], v[8:9], v[28:29]
	s_waitcnt vmcnt(1)
	v_pk_add_f32 v[16:17], v[58:59], 1.0 op_sel_hi:[1,0]
	v_pk_add_f32 v[26:27], v[56:57], 1.0 op_sel_hi:[1,0]
	s_waitcnt vmcnt(0)
	v_pk_fma_f32 v[8:9], v[8:9], v[16:17], v[62:63]
	v_pk_fma_f32 v[6:7], v[6:7], v[26:27], v[60:61]
	v_bfe_u32 v26, v8, 16, 1
	v_bfe_u32 v16, v6, 16, 1
	v_bfe_u32 v17, v7, 16, 1
	v_bfe_u32 v27, v9, 16, 1
	v_add3_u32 v6, v6, v16, s31
	v_add3_u32 v8, v8, v26, s31
	v_add3_u32 v7, v7, v17, s31
	v_add3_u32 v9, v9, v27, s31
	v_lshrrev_b32_e32 v6, 16, v6
	v_lshrrev_b32_e32 v8, 16, v8
	v_and_or_b32 v6, v7, s0, v6
	v_and_or_b32 v7, v9, s0, v8
	global_store_dwordx2 v[38:39], v[6:7], off offset:1536
	s_and_saveexec_b64 s[4:5], vcc
	s_cbranch_execz .LBB0_50
; DI unsigned pk2(float lo, float hi) { return f2bf(lo) | (f2bf(hi) << 16); }
; DI const float* modp(const unsigned char* ws, int layer, int who, int idx) { return (const float*)(ws + WS_MOD) + ((size_t)(layer * 9 + who) * 6 + idx) * D; }
; DI void phase_norm(int layer, const float* g, int sidx, bf16_t* dst, bool first) {
;     ...
;         for (int r = 0; r < 2; ++r) {
;             if (r == 1 && !has1) break;
;             const int m = r ? m1 : m0; const int b = m / T, t = m - b * T; const int who = t < LC ? 8 : b;
;             const float* sh = modp(ws, layer, who, sidx); const float* sc = modp(ws, layer, who, sidx + 1);
;             const float rstd = rsqrtf((r ? ss1 : ss0) * (1.f / D) + 1e-6f);
; #pragma unroll
;             for (int j = 0; j < 4; ++j) { const int c = 4 * lane + 256 * j;
;                 const f32x4 gg = *(const f32x4*)(g + c), s1 = *(const f32x4*)(sc + c), s0 = *(const f32x4*)(sh + c);
;                 f32x4 y = (r ? v1[j] : v0[j]) * rstd * gg; y = y * (s1 + 1.f) + s0;
;                 u32x2 w; w.x = pk2(y[0], y[1]); w.y = pk2(y[2], y[3]);
;                 *(u32x2*)(dst + (size_t)m * D + c) = w; }
	s_mov_b32 s2, 0x78787879
	v_mul_hi_i32 v6, v46, s2
	v_lshrrev_b32_e32 v7, 31, v6
	v_ashrrev_i32_e32 v6, 11, v6
	v_add_u32_e32 v6, v6, v7
	v_mul_i32_i24_e32 v7, 0xffffef00, v6
	v_add3_u32 v7, s24, v7, v30
	s_movk_i32 s2, 0xff
	v_cmp_lt_i32_e32 vcc, s2, v7
	s_mov_b64 s[2:3], 0x3000
	v_ashrrev_i32_e32 v47, 31, v46
	v_cndmask_b32_e32 v6, 8, v6, vcc
	v_add_u32_e32 v6, s25, v6
	v_mul_i32_i24_e32 v6, 6, v6
	v_ashrrev_i32_e32 v7, 31, v6
	v_lshlrev_b64 v[6:7], 12, v[6:7]
	v_lshl_add_u64 v[6:7], s[16:17], 0, v[6:7]
	v_lshl_add_u64 v[48:49], v[6:7], 0, s[2:3]
	s_mov_b64 s[2:3], 0x4000
	v_lshl_add_u64 v[60:61], v[6:7], 0, s[2:3]
	v_lshl_add_u64 v[16:17], v[60:61], 0, v[0:1]
	global_load_dwordx4 v[6:9], v[34:35], off
	global_load_dwordx4 v[26:29], v[16:17], off
	v_lshl_add_u64 v[16:17], v[48:49], 0, v[0:1]
	global_load_dwordx4 v[56:59], v[16:17], off
	s_waitcnt lgkmcnt(0)
	v_add_f32_e32 v0, v14, v15
	v_fmamk_f32 v0, v0, 0x3a800000, v183
	s_mov_b32 s2, 0x800000
	v_mul_f32_e32 v14, 0x4b800000, v0
	v_cmp_gt_f32_e32 vcc, s2, v0
	s_nop 1
	v_cndmask_b32_e32 v0, v0, v14, vcc
	v_rsq_f32_e32 v0, v0
	v_lshlrev_b64 v[14:15], 11, v[46:47]
	v_lshl_add_u64 v[46:47], v[36:37], 0, v[14:15]
	v_mul_f32_e32 v14, 0x45800000, v0
	v_cndmask_b32_e32 v0, v0, v14, vcc
	v_pk_mul_f32 v[14:15], v[24:25], v[0:1] op_sel_hi:[1,0]
	v_pk_mul_f32 v[16:17], v[22:23], v[0:1] op_sel_hi:[1,0]
	v_lshl_add_u64 v[22:23], v[48:49], 0, v[40:41]
	v_pk_mul_f32 v[20:21], v[20:21], v[0:1] op_sel_hi:[1,0]
	v_pk_mul_f32 v[18:19], v[18:19], v[0:1] op_sel_hi:[1,0]
	v_pk_mul_f32 v[12:13], v[12:13], v[0:1] op_sel_hi:[1,0]
	v_pk_mul_f32 v[10:11], v[10:11], v[0:1] op_sel_hi:[1,0]
	v_pk_mul_f32 v[4:5], v[4:5], v[0:1] op_sel_hi:[1,0]
	v_pk_mul_f32 v[2:3], v[2:3], v[0:1] op_sel_hi:[1,0]
	s_waitcnt vmcnt(2)
	v_pk_mul_f32 v[6:7], v[16:17], v[6:7]
	v_pk_mul_f32 v[8:9], v[14:15], v[8:9]
	s_waitcnt vmcnt(1)
	v_pk_add_f32 v[14:15], v[28:29], 1.0 op_sel_hi:[1,0]
	v_pk_add_f32 v[16:17], v[26:27], 1.0 op_sel_hi:[1,0]
	s_waitcnt vmcnt(0)
	v_pk_fma_f32 v[8:9], v[8:9], v[14:15], v[58:59]
	v_pk_fma_f32 v[6:7], v[6:7], v[16:17], v[56:57]
	v_bfe_u32 v16, v8, 16, 1
	v_bfe_u32 v14, v6, 16, 1
	v_bfe_u32 v15, v7, 16, 1
	v_bfe_u32 v17, v9, 16, 1
	v_add3_u32 v6, v6, v14, s31
	v_add3_u32 v8, v8, v16, s31
	v_add3_u32 v7, v7, v15, s31
	v_add3_u32 v9, v9, v17, s31
	v_lshrrev_b32_e32 v6, 16, v6
	v_lshrrev_b32_e32 v8, 16, v8
	v_and_or_b32 v6, v7, s0, v6
	v_and_or_b32 v7, v9, s0, v8
	v_lshl_add_u64 v[14:15], v[60:61], 0, v[40:41]
	global_load_dwordx4 v[80:83], v[34:35], off offset:1024
	global_store_dwordx2 v[46:47], v[6:7], off
	s_waitcnt vmcnt(1)
	v_mov_b64_e32 v[6:7], v[80:81]
	v_mov_b64_e32 v[8:9], v[82:83]
	v_pk_mul_f32 v[6:7], v[18:19], v[6:7]
	global_load_dwordx4 v[14:17], v[14:15], off
	v_pk_mul_f32 v[8:9], v[20:21], v[8:9]
	global_load_dwordx4 v[22:25], v[22:23], off
	v_lshl_add_u64 v[18:19], v[48:49], 0, v[42:43]
	s_waitcnt vmcnt(1)
	v_pk_add_f32 v[16:17], v[16:17], 1.0 op_sel_hi:[1,0]
	v_pk_add_f32 v[14:15], v[14:15], 1.0 op_sel_hi:[1,0]
	s_waitcnt vmcnt(0)
	v_pk_fma_f32 v[8:9], v[8:9], v[16:17], v[24:25]
	v_pk_fma_f32 v[6:7], v[6:7], v[14:15], v[22:23]
	v_bfe_u32 v16, v8, 16, 1
	v_bfe_u32 v14, v6, 16, 1
	v_bfe_u32 v15, v7, 16, 1
	v_bfe_u32 v17, v9, 16, 1
	v_add3_u32 v6, v6, v14, s31
	v_add3_u32 v8, v8, v16, s31
	v_add3_u32 v7, v7, v15, s31
	v_add3_u32 v9, v9, v17, s31
	v_lshrrev_b32_e32 v6, 16, v6
	v_lshrrev_b32_e32 v8, 16, v8
	v_and_or_b32 v6, v7, s0, v6
	v_and_or_b32 v7, v9, s0, v8
	v_lshl_add_u64 v[14:15], v[60:61], 0, v[42:43]
	global_load_dwordx4 v[80:83], v[34:35], off offset:2048
	global_store_dwordx2 v[46:47], v[6:7], off offset:512
	s_waitcnt vmcnt(1)
	v_mov_b64_e32 v[6:7], v[80:81]
	v_mov_b64_e32 v[8:9], v[82:83]
	v_pk_mul_f32 v[6:7], v[10:11], v[6:7]
	global_load_dwordx4 v[14:17], v[14:15], off
	v_pk_mul_f32 v[8:9], v[12:13], v[8:9]
	global_load_dwordx4 v[18:21], v[18:19], off
	s_waitcnt vmcnt(1)
	v_pk_add_f32 v[10:11], v[16:17], 1.0 op_sel_hi:[1,0]
	v_pk_add_f32 v[12:13], v[14:15], 1.0 op_sel_hi:[1,0]
	s_waitcnt vmcnt(0)
	v_pk_fma_f32 v[8:9], v[8:9], v[10:11], v[20:21]
	v_pk_fma_f32 v[6:7], v[6:7], v[12:13], v[18:19]
	v_bfe_u32 v12, v8, 16, 1
	v_bfe_u32 v10, v6, 16, 1
	v_bfe_u32 v11, v7, 16, 1
	v_bfe_u32 v13, v9, 16, 1
	v_add3_u32 v6, v6, v10, s31
	v_add3_u32 v8, v8, v12, s31
	v_add3_u32 v7, v7, v11, s31
	v_add3_u32 v9, v9, v13, s31
	v_lshrrev_b32_e32 v6, 16, v6
	v_lshrrev_b32_e32 v8, 16, v8
	v_and_or_b32 v6, v7, s0, v6
	v_and_or_b32 v7, v9, s0, v8
	v_lshl_add_u64 v[10:11], v[60:61], 0, v[44:45]
	global_load_dwordx4 v[80:83], v[34:35], off offset:3072
	v_lshl_add_u64 v[14:15], v[48:49], 0, v[44:45]
	global_load_dwordx4 v[84:87], v[10:11], off
	global_store_dwordx2 v[46:47], v[6:7], off offset:1024
	s_waitcnt vmcnt(2)
	v_mov_b64_e32 v[6:7], v[80:81]
	v_mov_b64_e32 v[8:9], v[82:83]
	v_pk_mul_f32 v[2:3], v[2:3], v[6:7]
	global_load_dwordx4 v[14:17], v[14:15], off
	v_pk_mul_f32 v[4:5], v[4:5], v[8:9]
	s_waitcnt vmcnt(2)
	v_mov_b64_e32 v[10:11], v[84:85]
	v_mov_b64_e32 v[12:13], v[86:87]
	v_pk_add_f32 v[6:7], v[12:13], 1.0 op_sel_hi:[1,0]
	v_pk_add_f32 v[8:9], v[10:11], 1.0 op_sel_hi:[1,0]
	s_waitcnt vmcnt(0)
	v_pk_fma_f32 v[4:5], v[4:5], v[6:7], v[16:17]
	v_pk_fma_f32 v[2:3], v[2:3], v[8:9], v[14:15]
	v_bfe_u32 v7, v4, 16, 1
	v_bfe_u32 v0, v2, 16, 1
	v_bfe_u32 v6, v3, 16, 1
	v_bfe_u32 v8, v5, 16, 1
	v_add3_u32 v0, v2, v0, s31
	v_add3_u32 v2, v3, v6, s31
	v_add3_u32 v3, v4, v7, s31
	v_add3_u32 v4, v5, v8, s31
	v_lshrrev_b32_e32 v0, 16, v0
	v_lshrrev_b32_e32 v3, 16, v3
	v_and_or_b32 v2, v2, s0, v0
	v_and_or_b32 v3, v4, s0, v3
	global_store_dwordx2 v[46:47], v[2:3], off offset:1536
	s_branch .LBB0_50

; DI unsigned pk2(float lo, float hi) { return f2bf(lo) | (f2bf(hi) << 16); }
; #define BIDX() sgpr_opaque((int)__builtin_amdgcn_workgroup_id_x())
; DI const float* modp(const unsigned char* ws, int layer, int who, int idx) { return (const float*)(ws + WS_MOD) + ((size_t)(layer * 9 + who) * 6 + idx) * D; }
; DI void phase_norm(int layer, const float* g, int sidx, bf16_t* dst, bool first) {
;     ...
;     for (int m0 = BIDX() * 8 + wave; m0 < M; m0 += 2 * nw) {
;         const int m1 = m0 + nw; const bool has1 = m1 < M; const int m1c = has1 ? m1 : m0;
;         const float* z0 = zrow_src(zcs, zls, m0); const float* z1 = zrow_src(zcs, zls, m1c);
;         f32x4 v0[4], v1[4]; float ss0 = 0.f, ss1 = 0.f;
; #pragma unroll
;         for (int j = 0; j < 4; ++j) { v0[j] = *(const f32x4*)(z0 + 4 * lane + 256 * j); v1[j] = *(const f32x4*)(z1 + 4 * lane + 256 * j); }
; #pragma unroll
;         for (int j = 0; j < 4; ++j) { ss0 += v0[j][0] * v0[j][0] + v0[j][1] * v0[j][1] + v0[j][2] * v0[j][2] + v0[j][3] * v0[j][3]; ss1 += v1[j][0] * v1[j][0] + v1[j][1] * v1[j][1] + v1[j][2] * v1[j][2] + v1[j][3] * v1[j][3]; }
; #pragma unroll
;         for (int o = 1; o < 64; o <<= 1) { ss0 += __shfl_xor(ss0, o); ss1 += __shfl_xor(ss1, o); }
; #pragma unroll
;         for (int r = 0; r < 2; ++r) {
;             if (r == 1 && !has1) break;
;             const int m = r ? m1 : m0; const int b = m / T, t = m - b * T; const int who = t < LC ? 8 : b;
;             const float* sh = modp(ws, layer, who, sidx); const float* sc = modp(ws, layer, who, sidx + 1);
;             const float rstd = rsqrtf((r ? ss1 : ss0) * (1.f / D) + 1e-6f);
; #pragma unroll
;             for (int j = 0; j < 4; ++j) { const int c = 4 * lane + 256 * j;
;                 const f32x4 gg = *(const f32x4*)(g + c), s1 = *(const f32x4*)(sc + c), s0 = *(const f32x4*)(sh + c);
;                 f32x4 y = (r ? v1[j] : v0[j]) * rstd * gg; y = y * (s1 + 1.f) + s0;
;                 u32x2 w; w.x = pk2(y[0], y[1]); w.y = pk2(y[2], y[3]);
;                 *(u32x2*)(dst + (size_t)m * D + c) = w; }
.LBB0_759:
	s_mov_b32 s2, 0x78787879
	v_mul_hi_i32 v0, v30, s2
	v_lshrrev_b32_e32 v2, 31, v0
	v_ashrrev_i32_e32 v0, 11, v0
	v_add_u32_e32 v3, v0, v2
	s_movk_i32 s2, 0xef00
	v_mad_i32_i24 v0, v3, s2, v30
	s_movk_i32 s2, 0x100
	v_cmp_gt_i32_e64 s[4:5], s2, v0
	s_movk_i32 s2, 0xff
	v_cmp_lt_i32_e32 vcc, s2, v0
	s_and_saveexec_b64 s[2:3], vcc
	s_xor_b64 s[2:3], exec, s[2:3]
	v_mul_i32_i24_e32 v0, 0xffffef00, v3
	v_lshl_add_u32 v0, v3, 12, v0
	s_movk_i32 s6, 0xff00
	v_add3_u32 v6, v30, v0, s6
	s_or_saveexec_b64 s[2:3], s[2:3]
	s_waitcnt lgkmcnt(0)
	v_mov_b64_e32 v[8:9], s[12:13]
	s_xor_b64 exec, exec, s[2:3]
	v_lshl_add_u32 v6, v3, 8, v0
	v_mov_b64_e32 v[8:9], s[8:9]
	s_or_b64 exec, exec, s[2:3]
	v_add_u32_e32 v46, s22, v30
	s_mov_b32 s2, 0x8800
	v_cmp_gt_i32_e32 vcc, s2, v46
	s_mov_b32 s2, 0x78787879
	s_nop 0
	v_cndmask_b32_e32 v2, v30, v46, vcc
	v_mul_hi_i32 v0, v2, s2
	v_lshrrev_b32_e32 v4, 31, v0
	v_ashrrev_i32_e32 v0, 11, v0
	v_add_u32_e32 v0, v0, v4
	s_movk_i32 s2, 0xef00
	v_mad_i32_i24 v7, v0, s2, v2
	s_movk_i32 s2, 0xff
	v_cmp_lt_i32_e64 s[6:7], s2, v7
	s_and_saveexec_b64 s[2:3], s[6:7]
	s_xor_b64 s[2:3], exec, s[2:3]
	v_lshlrev_b32_e32 v0, 12, v0
	s_movk_i32 s6, 0xff00
	v_add3_u32 v2, v0, v7, s6
	s_or_saveexec_b64 s[2:3], s[2:3]
	v_mov_b64_e32 v[4:5], s[12:13]
	s_xor_b64 exec, exec, s[2:3]
	v_lshl_add_u32 v2, v0, 8, v7
	v_mov_b64_e32 v[4:5], s[8:9]
	s_or_b64 exec, exec, s[2:3]
	v_ashrrev_i32_e32 v7, 31, v6
	v_lshlrev_b64 v[6:7], 12, v[6:7]
	v_lshl_add_u64 v[6:7], v[8:9], 0, v[6:7]
	v_lshlrev_b32_e32 v0, 2, v32
	v_lshl_add_u64 v[6:7], v[6:7], 0, v[0:1]
	global_load_dwordx4 v[54:57], v[6:7], off
	global_load_dwordx4 v[26:29], v[6:7], off offset:1024
	global_load_dwordx4 v[14:17], v[6:7], off offset:2048
	s_nop 0
	global_load_dwordx4 v[6:9], v[6:7], off offset:3072
	v_cndmask_b32_e64 v3, v3, 8, s[4:5]
	v_add_u32_e32 v3, s23, v3
	v_mul_i32_i24_e32 v10, 6, v3
	v_ashrrev_i32_e32 v11, 31, v10
	v_lshlrev_b64 v[10:11], 12, v[10:11]
	v_lshl_add_u64 v[10:11], s[14:15], 0, v[10:11]
	s_mov_b64 s[2:3], 0x1000
	v_lshl_add_u64 v[70:71], v[10:11], 0, s[2:3]
	v_lshl_add_u64 v[12:13], v[70:71], 0, v[0:1]
	global_load_dwordx4 v[58:61], v[12:13], off
	global_load_dwordx4 v[62:65], v[34:35], off
	v_lshl_add_u64 v[72:73], v[10:11], 0, v[0:1]
	global_load_dwordx4 v[66:69], v[72:73], off
	s_mov_b32 s2, 0x800000
	v_mov_b32_e32 v41, v1
	s_waitcnt vmcnt(6)
	v_mov_b32_e32 v12, v55
	s_waitcnt vmcnt(5)
	v_mov_b32_e32 v13, v27
	v_mov_b32_e32 v10, v54
	v_mov_b32_e32 v11, v26
	s_waitcnt vmcnt(4)
	v_mov_b32_e32 v24, v15
	s_waitcnt vmcnt(3)
	v_mov_b32_e32 v25, v7
	v_pk_mul_f32 v[12:13], v[12:13], v[12:13]
	v_mov_b32_e32 v18, v56
	v_mov_b32_e32 v19, v28
	v_mov_b32_e32 v22, v14
	v_mov_b32_e32 v23, v6
	v_pk_mul_f32 v[24:25], v[24:25], v[24:25]
	v_pk_fma_f32 v[10:11], v[10:11], v[10:11], v[12:13]
	v_mov_b32_e32 v20, v57
	v_mov_b32_e32 v21, v29
	v_mov_b32_e32 v74, v16
	v_mov_b32_e32 v75, v8
	v_pk_fma_f32 v[12:13], v[22:23], v[22:23], v[24:25]
	v_pk_fma_f32 v[10:11], v[18:19], v[18:19], v[10:11]
	v_mov_b32_e32 v76, v17
	v_mov_b32_e32 v77, v9
	v_pk_fma_f32 v[12:13], v[74:75], v[74:75], v[12:13]
	v_pk_fma_f32 v[10:11], v[20:21], v[20:21], v[10:11]
	v_pk_fma_f32 v[12:13], v[76:77], v[76:77], v[12:13]
	v_add_f32_e32 v3, v10, v11
	v_add_f32_e32 v3, v3, v12
	v_add_f32_e32 v3, v3, v13
	ds_bpermute_b32 v10, v33, v3
	s_waitcnt vmcnt(2)
	v_pk_add_f32 v[60:61], v[60:61], 1.0 op_sel_hi:[1,0]
	v_pk_add_f32 v[58:59], v[58:59], 1.0 op_sel_hi:[1,0]
	s_waitcnt lgkmcnt(0)
	v_add_f32_e32 v3, v3, v10
	ds_bpermute_b32 v10, v48, v3
	s_waitcnt lgkmcnt(0)
	v_add_f32_e32 v3, v3, v10
	ds_bpermute_b32 v10, v49, v3
	s_waitcnt lgkmcnt(0)
	v_add_f32_e32 v3, v3, v10
	ds_bpermute_b32 v10, v50, v3
	s_waitcnt lgkmcnt(0)
	v_add_f32_e32 v10, v3, v10
	ds_bpermute_b32 v11, v51, v10
	v_ashrrev_i32_e32 v3, 31, v2
	v_lshlrev_b64 v[2:3], 12, v[2:3]
	v_lshl_add_u64 v[2:3], v[4:5], 0, v[2:3]
	v_lshl_add_u64 v[2:3], v[2:3], 0, v[0:1]
	s_waitcnt lgkmcnt(0)
	v_add_f32_e32 v10, v10, v11
	ds_bpermute_b32 v11, v52, v10
	global_load_dwordx4 v[22:25], v[2:3], off
	global_load_dwordx4 v[18:21], v[2:3], off offset:1024
	s_waitcnt lgkmcnt(0)
	v_add_f32_e32 v4, v10, v11
	v_fmamk_f32 v4, v4, 0x3a800000, v183
	v_mul_f32_e32 v5, 0x4b800000, v4
	v_cmp_gt_f32_e64 s[4:5], s2, v4
	s_nop 1
	v_cndmask_b32_e64 v4, v4, v5, s[4:5]
	v_rsq_f32_e32 v31, v4
	global_load_dwordx4 v[10:13], v[2:3], off offset:2048
	s_nop 0
	global_load_dwordx4 v[2:5], v[2:3], off offset:3072
	v_mul_f32_e32 v43, 0x45800000, v31
	v_cndmask_b32_e64 v74, v31, v43, s[4:5]
	v_pk_mul_f32 v[56:57], v[56:57], v[74:75] op_sel_hi:[1,0]
	v_pk_mul_f32 v[54:55], v[54:55], v[74:75] op_sel_hi:[1,0]
	s_waitcnt vmcnt(5)
	v_pk_mul_f32 v[56:57], v[64:65], v[56:57]
	v_pk_mul_f32 v[54:55], v[62:63], v[54:55]
	s_waitcnt vmcnt(4)
	v_pk_fma_f32 v[56:57], v[60:61], v[56:57], v[68:69]
	v_pk_fma_f32 v[54:55], v[58:59], v[54:55], v[66:67]
	v_bfe_u32 v45, v56, 16, 1
	v_bfe_u32 v31, v54, 16, 1
	v_bfe_u32 v43, v55, 16, 1
	v_bfe_u32 v47, v57, 16, 1
	v_add3_u32 v31, v54, v31, s31
	v_add3_u32 v45, v56, v45, s31
	v_add3_u32 v43, v55, v43, s31
	v_add3_u32 v47, v57, v47, s31
	v_lshrrev_b32_e32 v31, 16, v31
	v_lshrrev_b32_e32 v45, 16, v45
	v_and_or_b32 v54, v43, s0, v31
	v_and_or_b32 v55, v47, s0, v45
	global_load_dwordx4 v[80:83], v[34:35], off offset:1024
	v_lshl_add_u64 v[58:59], v[70:71], 0, v[40:41]
	global_load_dwordx4 v[84:87], v[58:59], off
	s_nop 0
	global_load_dwordx4 v[88:91], v[72:73], off offset:1024
	v_pk_mul_f32 v[28:29], v[28:29], v[74:75] op_sel_hi:[1,0]
	v_pk_mul_f32 v[26:27], v[26:27], v[74:75] op_sel_hi:[1,0]
	v_mov_b32_e32 v43, v1
	v_pk_mul_f32 v[16:17], v[16:17], v[74:75] op_sel_hi:[1,0]
	v_pk_mul_f32 v[14:15], v[14:15], v[74:75] op_sel_hi:[1,0]
	v_pk_mul_f32 v[8:9], v[8:9], v[74:75] op_sel_hi:[1,0]
	v_pk_mul_f32 v[6:7], v[6:7], v[74:75] op_sel_hi:[1,0]
	global_store_dwordx2 v[38:39], v[54:55], off
	s_waitcnt vmcnt(3)
; DI unsigned pk2(float lo, float hi) { return f2bf(lo) | (f2bf(hi) << 16); }
; DI const float* modp(const unsigned char* ws, int layer, int who, int idx) { return (const float*)(ws + WS_MOD) + ((size_t)(layer * 9 + who) * 6 + idx) * D; }
; DI void phase_norm(int layer, const float* g, int sidx, bf16_t* dst, bool first) {
;     ...
;         for (int o = 1; o < 64; o <<= 1) { ss0 += __shfl_xor(ss0, o); ss1 += __shfl_xor(ss1, o); }
; #pragma unroll
;         for (int r = 0; r < 2; ++r) {
;             if (r == 1 && !has1) break;
;             const int m = r ? m1 : m0; const int b = m / T, t = m - b * T; const int who = t < LC ? 8 : b;
;             const float* sh = modp(ws, layer, who, sidx); const float* sc = modp(ws, layer, who, sidx + 1);
;             const float rstd = rsqrtf((r ? ss1 : ss0) * (1.f / D) + 1e-6f);
; #pragma unroll
;             for (int j = 0; j < 4; ++j) { const int c = 4 * lane + 256 * j;
;                 const f32x4 gg = *(const f32x4*)(g + c), s1 = *(const f32x4*)(sc + c), s0 = *(const f32x4*)(sh + c);
;                 f32x4 y = (r ? v1[j] : v0[j]) * rstd * gg; y = y * (s1 + 1.f) + s0;
;                 u32x2 w; w.x = pk2(y[0], y[1]); w.y = pk2(y[2], y[3]);
;                 *(u32x2*)(dst + (size_t)m * D + c) = w; }
	v_mov_b64_e32 v[54:55], v[80:81]
	v_mov_b64_e32 v[56:57], v[82:83]
	v_pk_mul_f32 v[26:27], v[54:55], v[26:27]
	v_pk_mul_f32 v[28:29], v[56:57], v[28:29]
	s_waitcnt vmcnt(2)
	v_mov_b64_e32 v[58:59], v[84:85]
	v_mov_b64_e32 v[60:61], v[86:87]
	v_pk_add_f32 v[54:55], v[60:61], 1.0 op_sel_hi:[1,0]
	v_pk_add_f32 v[56:57], v[58:59], 1.0 op_sel_hi:[1,0]
	s_waitcnt vmcnt(1)
	v_mov_b64_e32 v[62:63], v[88:89]
	v_mov_b64_e32 v[64:65], v[90:91]
	v_pk_fma_f32 v[28:29], v[54:55], v[28:29], v[64:65]
	v_pk_fma_f32 v[26:27], v[56:57], v[26:27], v[62:63]
	v_bfe_u32 v47, v28, 16, 1
	v_bfe_u32 v31, v26, 16, 1
	v_bfe_u32 v45, v27, 16, 1
	v_bfe_u32 v53, v29, 16, 1
	v_add3_u32 v26, v26, v31, s31
	v_add3_u32 v28, v28, v47, s31
	v_add3_u32 v27, v27, v45, s31
	v_add3_u32 v29, v29, v53, s31
	v_lshrrev_b32_e32 v26, 16, v26
	v_lshrrev_b32_e32 v28, 16, v28
	v_and_or_b32 v26, v27, s0, v26
	v_and_or_b32 v27, v29, s0, v28
	global_load_dwordx4 v[80:83], v[34:35], off offset:2048
	v_lshl_add_u64 v[54:55], v[70:71], 0, v[42:43]
	global_load_dwordx4 v[84:87], v[54:55], off
	s_nop 0
	global_load_dwordx4 v[88:91], v[72:73], off offset:2048
	v_mov_b32_e32 v45, v1
	global_store_dwordx2 v[38:39], v[26:27], off offset:512
	s_waitcnt vmcnt(3)
	v_mov_b64_e32 v[26:27], v[80:81]
	v_mov_b64_e32 v[28:29], v[82:83]
	v_pk_mul_f32 v[14:15], v[26:27], v[14:15]
	v_pk_mul_f32 v[16:17], v[28:29], v[16:17]
	s_waitcnt vmcnt(2)
	v_mov_b64_e32 v[54:55], v[84:85]
	v_mov_b64_e32 v[56:57], v[86:87]
	v_pk_add_f32 v[26:27], v[56:57], 1.0 op_sel_hi:[1,0]
	v_pk_add_f32 v[28:29], v[54:55], 1.0 op_sel_hi:[1,0]
	s_waitcnt vmcnt(1)
	v_mov_b64_e32 v[58:59], v[88:89]
	v_mov_b64_e32 v[60:61], v[90:91]
	v_pk_fma_f32 v[16:17], v[26:27], v[16:17], v[60:61]
	v_pk_fma_f32 v[14:15], v[28:29], v[14:15], v[58:59]
	v_bfe_u32 v28, v16, 16, 1
	v_bfe_u32 v26, v14, 16, 1
	v_bfe_u32 v27, v15, 16, 1
	v_bfe_u32 v29, v17, 16, 1
	v_add3_u32 v14, v14, v26, s31
	v_add3_u32 v16, v16, v28, s31
	v_add3_u32 v15, v15, v27, s31
	v_add3_u32 v17, v17, v29, s31
	v_lshrrev_b32_e32 v14, 16, v14
	v_lshrrev_b32_e32 v16, 16, v16
	v_and_or_b32 v14, v15, s0, v14
	v_and_or_b32 v15, v17, s0, v16
	global_store_dwordx2 v[38:39], v[14:15], off offset:1024
	global_load_dwordx4 v[26:29], v[34:35], off offset:3072
	v_lshl_add_u64 v[14:15], v[70:71], 0, v[44:45]
	global_load_dwordx4 v[54:57], v[14:15], off
	global_load_dwordx4 v[58:61], v[72:73], off offset:3072
	v_mul_f32_e32 v14, v23, v23
	v_mul_f32_e32 v15, v19, v19
	v_mul_f32_e32 v16, v11, v11
	v_fmac_f32_e32 v14, v22, v22
	v_fmac_f32_e32 v15, v18, v18
	v_mul_f32_e32 v17, v3, v3
	v_fmac_f32_e32 v16, v10, v10
	v_fmac_f32_e32 v14, v24, v24
	v_fmac_f32_e32 v15, v20, v20
	v_fmac_f32_e32 v17, v2, v2
	v_fmac_f32_e32 v16, v12, v12
	v_fmac_f32_e32 v14, v25, v25
	v_fmac_f32_e32 v15, v21, v21
	v_fmac_f32_e32 v17, v4, v4
	v_fmac_f32_e32 v16, v13, v13
	v_add_f32_e32 v14, v14, v15
	v_fmac_f32_e32 v17, v5, v5
	v_add_f32_e32 v14, v14, v16
	v_add_f32_e32 v14, v14, v17
	ds_bpermute_b32 v15, v33, v14
	s_waitcnt lgkmcnt(0)
	v_add_f32_e32 v14, v14, v15
	ds_bpermute_b32 v15, v48, v14
	s_waitcnt lgkmcnt(0)
	v_add_f32_e32 v14, v14, v15
	ds_bpermute_b32 v15, v49, v14
	s_waitcnt lgkmcnt(0)
	v_add_f32_e32 v14, v14, v15
	ds_bpermute_b32 v15, v50, v14
	s_waitcnt lgkmcnt(0)
	v_add_f32_e32 v14, v14, v15
	ds_bpermute_b32 v15, v51, v14
	s_waitcnt lgkmcnt(0)
	v_add_f32_e32 v14, v14, v15
	ds_bpermute_b32 v15, v52, v14
	s_waitcnt vmcnt(2)
	v_pk_mul_f32 v[6:7], v[6:7], v[26:27]
	v_pk_mul_f32 v[8:9], v[8:9], v[28:29]
	s_waitcnt vmcnt(1)
	v_pk_add_f32 v[16:17], v[56:57], 1.0 op_sel_hi:[1,0]
	v_pk_add_f32 v[26:27], v[54:55], 1.0 op_sel_hi:[1,0]
	s_waitcnt vmcnt(0)
	v_pk_fma_f32 v[8:9], v[8:9], v[16:17], v[60:61]
	v_pk_fma_f32 v[6:7], v[6:7], v[26:27], v[58:59]
	v_bfe_u32 v26, v8, 16, 1
	v_bfe_u32 v16, v6, 16, 1
	v_bfe_u32 v17, v7, 16, 1
	v_bfe_u32 v27, v9, 16, 1
	v_add3_u32 v6, v6, v16, s31
	v_add3_u32 v8, v8, v26, s31
	v_add3_u32 v7, v7, v17, s31
	v_add3_u32 v9, v9, v27, s31
	v_lshrrev_b32_e32 v6, 16, v6
	v_lshrrev_b32_e32 v8, 16, v8
	v_and_or_b32 v6, v7, s0, v6
	v_and_or_b32 v7, v9, s0, v8
	global_store_dwordx2 v[38:39], v[6:7], off offset:1536
	s_and_saveexec_b64 s[4:5], vcc
	s_cbranch_execz .LBB0_758
; DI unsigned pk2(float lo, float hi) { return f2bf(lo) | (f2bf(hi) << 16); }
; DI const float* modp(const unsigned char* ws, int layer, int who, int idx) { return (const float*)(ws + WS_MOD) + ((size_t)(layer * 9 + who) * 6 + idx) * D; }
; DI void phase_norm(int layer, const float* g, int sidx, bf16_t* dst, bool first) {
;     ...
;         for (int r = 0; r < 2; ++r) {
;             if (r == 1 && !has1) break;
;             const int m = r ? m1 : m0; const int b = m / T, t = m - b * T; const int who = t < LC ? 8 : b;
;             const float* sh = modp(ws, layer, who, sidx); const float* sc = modp(ws, layer, who, sidx + 1);
;             const float rstd = rsqrtf((r ? ss1 : ss0) * (1.f / D) + 1e-6f);
; #pragma unroll
;             for (int j = 0; j < 4; ++j) { const int c = 4 * lane + 256 * j;
;                 const f32x4 gg = *(const f32x4*)(g + c), s1 = *(const f32x4*)(sc + c), s0 = *(const f32x4*)(sh + c);
;                 f32x4 y = (r ? v1[j] : v0[j]) * rstd * gg; y = y * (s1 + 1.f) + s0;
;                 u32x2 w; w.x = pk2(y[0], y[1]); w.y = pk2(y[2], y[3]);
;                 *(u32x2*)(dst + (size_t)m * D + c) = w; }
	s_mov_b32 s2, 0x78787879
	v_mul_hi_i32 v6, v46, s2
	v_lshrrev_b32_e32 v7, 31, v6
	v_ashrrev_i32_e32 v6, 11, v6
	v_add_u32_e32 v6, v6, v7
	v_mul_i32_i24_e32 v7, 0xffffef00, v6
	v_add3_u32 v7, s22, v7, v30
	s_movk_i32 s2, 0xff
	v_cmp_lt_i32_e32 vcc, s2, v7
	s_mov_b64 s[2:3], 0x1000
	v_ashrrev_i32_e32 v47, 31, v46
	v_cndmask_b32_e32 v6, 8, v6, vcc
	v_add_u32_e32 v6, s23, v6
	v_mul_i32_i24_e32 v6, 6, v6
	v_ashrrev_i32_e32 v7, 31, v6
	v_lshlrev_b64 v[6:7], 12, v[6:7]
	v_lshl_add_u64 v[16:17], s[14:15], 0, v[6:7]
	v_lshl_add_u64 v[58:59], v[16:17], 0, s[2:3]
	v_lshl_add_u64 v[26:27], v[58:59], 0, v[0:1]
	global_load_dwordx4 v[6:9], v[34:35], off
	v_lshl_add_u64 v[60:61], v[16:17], 0, v[0:1]
	global_load_dwordx4 v[26:29], v[26:27], off
	s_waitcnt lgkmcnt(0)
	v_add_f32_e32 v0, v14, v15
	global_load_dwordx4 v[54:57], v[60:61], off
	v_fmamk_f32 v0, v0, 0x3a800000, v183
	s_mov_b32 s2, 0x800000
	v_mul_f32_e32 v14, 0x4b800000, v0
	v_cmp_gt_f32_e32 vcc, s2, v0
	s_nop 1
	v_cndmask_b32_e32 v0, v0, v14, vcc
	v_rsq_f32_e32 v0, v0
	v_lshlrev_b64 v[14:15], 11, v[46:47]
	v_lshl_add_u64 v[46:47], v[36:37], 0, v[14:15]
	v_mul_f32_e32 v14, 0x45800000, v0
	v_cndmask_b32_e32 v0, v0, v14, vcc
	v_pk_mul_f32 v[14:15], v[24:25], v[0:1] op_sel_hi:[1,0]
	v_pk_mul_f32 v[16:17], v[22:23], v[0:1] op_sel_hi:[1,0]
	v_pk_mul_f32 v[20:21], v[20:21], v[0:1] op_sel_hi:[1,0]
	v_pk_mul_f32 v[18:19], v[18:19], v[0:1] op_sel_hi:[1,0]
	v_pk_mul_f32 v[12:13], v[12:13], v[0:1] op_sel_hi:[1,0]
	v_pk_mul_f32 v[10:11], v[10:11], v[0:1] op_sel_hi:[1,0]
	v_pk_mul_f32 v[4:5], v[4:5], v[0:1] op_sel_hi:[1,0]
	v_pk_mul_f32 v[2:3], v[2:3], v[0:1] op_sel_hi:[1,0]
	s_waitcnt vmcnt(2)
	v_pk_mul_f32 v[6:7], v[16:17], v[6:7]
	v_pk_mul_f32 v[8:9], v[14:15], v[8:9]
	s_waitcnt vmcnt(1)
	v_pk_add_f32 v[14:15], v[28:29], 1.0 op_sel_hi:[1,0]
	v_pk_add_f32 v[16:17], v[26:27], 1.0 op_sel_hi:[1,0]
	s_waitcnt vmcnt(0)
	v_pk_fma_f32 v[8:9], v[8:9], v[14:15], v[56:57]
	v_pk_fma_f32 v[6:7], v[6:7], v[16:17], v[54:55]
	v_bfe_u32 v16, v8, 16, 1
	v_bfe_u32 v14, v6, 16, 1
	v_bfe_u32 v15, v7, 16, 1
	v_bfe_u32 v17, v9, 16, 1
	v_add3_u32 v6, v6, v14, s31
	v_add3_u32 v8, v8, v16, s31
	v_add3_u32 v7, v7, v15, s31
	v_add3_u32 v9, v9, v17, s31
	v_lshrrev_b32_e32 v6, 16, v6
	v_lshrrev_b32_e32 v8, 16, v8
	v_and_or_b32 v6, v7, s0, v6
	v_and_or_b32 v7, v9, s0, v8
	global_load_dwordx4 v[80:83], v[34:35], off offset:1024
	v_lshl_add_u64 v[14:15], v[58:59], 0, v[40:41]
	global_load_dwordx4 v[84:87], v[14:15], off
	s_nop 0
	global_load_dwordx4 v[88:91], v[60:61], off offset:1024
	global_store_dwordx2 v[46:47], v[6:7], off
	s_waitcnt vmcnt(3)
	v_mov_b64_e32 v[6:7], v[80:81]
	v_mov_b64_e32 v[8:9], v[82:83]
	v_pk_mul_f32 v[6:7], v[18:19], v[6:7]
	v_pk_mul_f32 v[8:9], v[20:21], v[8:9]
	s_waitcnt vmcnt(2)
	v_mov_b64_e32 v[14:15], v[84:85]
	v_mov_b64_e32 v[16:17], v[86:87]
	v_pk_add_f32 v[16:17], v[16:17], 1.0 op_sel_hi:[1,0]
	v_pk_add_f32 v[14:15], v[14:15], 1.0 op_sel_hi:[1,0]
	s_waitcnt vmcnt(1)
	v_mov_b64_e32 v[22:23], v[88:89]
	v_mov_b64_e32 v[24:25], v[90:91]
	v_pk_fma_f32 v[8:9], v[8:9], v[16:17], v[24:25]
	v_pk_fma_f32 v[6:7], v[6:7], v[14:15], v[22:23]
	v_bfe_u32 v16, v8, 16, 1
	v_bfe_u32 v14, v6, 16, 1
	v_bfe_u32 v15, v7, 16, 1
	v_bfe_u32 v17, v9, 16, 1
	v_add3_u32 v6, v6, v14, s31
	v_add3_u32 v8, v8, v16, s31
	v_add3_u32 v7, v7, v15, s31
	v_add3_u32 v9, v9, v17, s31
	v_lshrrev_b32_e32 v6, 16, v6
	v_lshrrev_b32_e32 v8, 16, v8
	v_and_or_b32 v6, v7, s0, v6
	v_and_or_b32 v7, v9, s0, v8
	global_load_dwordx4 v[80:83], v[34:35], off offset:2048
	v_lshl_add_u64 v[14:15], v[58:59], 0, v[42:43]
	global_load_dwordx4 v[84:87], v[14:15], off
	s_nop 0
	global_load_dwordx4 v[88:91], v[60:61], off offset:2048
	global_store_dwordx2 v[46:47], v[6:7], off offset:512
	s_waitcnt vmcnt(3)
	v_mov_b64_e32 v[6:7], v[80:81]
	v_mov_b64_e32 v[8:9], v[82:83]
	v_pk_mul_f32 v[6:7], v[10:11], v[6:7]
	v_pk_mul_f32 v[8:9], v[12:13], v[8:9]
	s_waitcnt vmcnt(2)
	v_mov_b64_e32 v[14:15], v[84:85]
	v_mov_b64_e32 v[16:17], v[86:87]
	v_pk_add_f32 v[10:11], v[16:17], 1.0 op_sel_hi:[1,0]
	v_pk_add_f32 v[12:13], v[14:15], 1.0 op_sel_hi:[1,0]
	s_waitcnt vmcnt(1)
	v_mov_b64_e32 v[18:19], v[88:89]
	v_mov_b64_e32 v[20:21], v[90:91]
	v_pk_fma_f32 v[8:9], v[8:9], v[10:11], v[20:21]
	v_pk_fma_f32 v[6:7], v[6:7], v[12:13], v[18:19]
	v_bfe_u32 v12, v8, 16, 1
	v_bfe_u32 v10, v6, 16, 1
	v_bfe_u32 v11, v7, 16, 1
	v_bfe_u32 v13, v9, 16, 1
	v_add3_u32 v6, v6, v10, s31
	v_add3_u32 v8, v8, v12, s31
	v_add3_u32 v7, v7, v11, s31
	v_add3_u32 v9, v9, v13, s31
	v_lshrrev_b32_e32 v6, 16, v6
	v_lshrrev_b32_e32 v8, 16, v8
	v_and_or_b32 v6, v7, s0, v6
	v_and_or_b32 v7, v9, s0, v8
	global_load_dwordx4 v[80:83], v[34:35], off offset:3072
	v_lshl_add_u64 v[10:11], v[58:59], 0, v[44:45]
	global_load_dwordx4 v[84:87], v[10:11], off
	s_nop 0
	global_load_dwordx4 v[88:91], v[60:61], off offset:3072
	global_store_dwordx2 v[46:47], v[6:7], off offset:1024
	s_waitcnt vmcnt(3)
	v_mov_b64_e32 v[6:7], v[80:81]
	v_mov_b64_e32 v[8:9], v[82:83]
	v_pk_mul_f32 v[2:3], v[2:3], v[6:7]
	v_pk_mul_f32 v[4:5], v[4:5], v[8:9]
	s_waitcnt vmcnt(2)
	v_mov_b64_e32 v[10:11], v[84:85]
	v_mov_b64_e32 v[12:13], v[86:87]
	v_pk_add_f32 v[6:7], v[12:13], 1.0 op_sel_hi:[1,0]
	v_pk_add_f32 v[8:9], v[10:11], 1.0 op_sel_hi:[1,0]
	s_waitcnt vmcnt(1)
	v_mov_b64_e32 v[14:15], v[88:89]
	v_mov_b64_e32 v[16:17], v[90:91]
	v_pk_fma_f32 v[4:5], v[4:5], v[6:7], v[16:17]
	v_pk_fma_f32 v[2:3], v[2:3], v[8:9], v[14:15]
	v_bfe_u32 v7, v4, 16, 1
	v_bfe_u32 v0, v2, 16, 1
	v_bfe_u32 v6, v3, 16, 1
	v_bfe_u32 v8, v5, 16, 1
	v_add3_u32 v0, v2, v0, s31
	v_add3_u32 v2, v3, v6, s31
	v_add3_u32 v3, v4, v7, s31
	v_add3_u32 v4, v5, v8, s31
	v_lshrrev_b32_e32 v0, 16, v0
	v_lshrrev_b32_e32 v3, 16, v3
	v_and_or_b32 v2, v2, s0, v0
	v_and_or_b32 v3, v4, s0, v3
	global_store_dwordx2 v[46:47], v[2:3], off offset:1536
	s_branch .LBB0_758
